# P5 out-proj epilogue: all 16 x1b loads preloaded up front, per-step vmcnt(1) drains removed
# baseline (speedup 1.0000x reference)
; __device__ __forceinline__ unsigned cvt_pk_bf16(float lo, float hi) { unsigned r; asm volatile("v_cvt_pk_bf16_f32 %0, %1, %2" : "=v"(r) : "v"(lo), "v"(hi)); return r; }
;     __device__ __forceinline__ void operator()(const f32x4 (&acc)[2][2][4][2], const Unit& u, int wr, int wc, int fr, int fq) const {
;         const int col0 = u.pn * BM + wc * 32 + 8 * fq;
; #pragma unroll
;         for (int ai = 0; ai < 2; ++ai)
; #pragma unroll
;             for (int m = 0; m < 4; ++m) { const int rt = ai * HALF + wr * 64 + m * 16 + fr; const float r = tab[256 + rt]; const size_t off = (size_t)(u.pm * BM + rt) * 1024 + col0;
; #pragma unroll
;                 for (int bj = 0; bj < 2; ++bj) {
;                     const u32x4 xw = *(const u32x4*)(x1b + off + bj * HALF);
;                     f32x4 x0, x1;
;                     x0[0] = __uint_as_float(xw.x << 16); x0[1] = __uint_as_float(xw.x & 0xffff0000u); x0[2] = __uint_as_float(xw.y << 16); x0[3] = __uint_as_float(xw.y & 0xffff0000u);
;                     x1[0] = __uint_as_float(xw.z << 16); x1[1] = __uint_as_float(xw.z & 0xffff0000u); x1[2] = __uint_as_float(xw.w << 16); x1[3] = __uint_as_float(xw.w & 0xffff0000u);
;                     const f32x4 v0 = x0 + acc[ai][bj][m][0] * r, v1 = x1 + acc[ai][bj][m][1] * r;
;                     u32x4 w; w.x = cvt_pk_bf16(v0[0], v0[1]); w.y = cvt_pk_bf16(v0[2], v0[3]); w.z = cvt_pk_bf16(v1[0], v1[1]); w.w = cvt_pk_bf16(v1[2], v1[3]);
;                     *(u32x4*)(x1b + off + bj * HALF) = w; } }
;     }
.LBB0_879:
	s_add_u32 s24, s96, 0x1400000
	s_addc_u32 s25, s97, 0
	v_ashrrev_i32_e32 v128, 1, v143
	s_lshl_b32 s8, s8, 8
	v_and_b32_e32 v128, -8, v128
	s_or_b32 s8, s8, s52
	v_add_u32_e32 v130, s6, v142
	v_add_u32_e32 v128, s8, v128
	v_ashrrev_i32_e32 v131, 31, v130
	v_ashrrev_i32_e32 v129, 31, v128
	v_lshlrev_b64 v[132:133], 11, v[130:131]
	v_lshl_add_u64 v[132:133], s[24:25], 0, v[132:133]
	v_lshlrev_b64 v[128:129], 1, v[128:129]
	v_lshl_add_u64 v[144:145], v[132:133], 0, v[128:129]
	s_mov_b32 s99, 0
	global_load_dwordx4 v[152:155], v[144:145], off
	global_load_dwordx4 v[156:159], v[144:145], off offset:256
	s_mov_b32 s98, 0x8000
	v_lshl_add_u64 v[216:217], v[144:145], 0, s[98:99]
	global_load_dwordx4 v[160:163], v[216:217], off
	global_load_dwordx4 v[164:167], v[216:217], off offset:256
	s_mov_b32 s98, 0x10000
	v_lshl_add_u64 v[216:217], v[144:145], 0, s[98:99]
	global_load_dwordx4 v[168:171], v[216:217], off
	global_load_dwordx4 v[172:175], v[216:217], off offset:256
	s_mov_b32 s98, 0x18000
	v_lshl_add_u64 v[216:217], v[144:145], 0, s[98:99]
	global_load_dwordx4 v[176:179], v[216:217], off
	global_load_dwordx4 v[180:183], v[216:217], off offset:256
	s_mov_b32 s98, 0x40000
	v_lshl_add_u64 v[216:217], v[144:145], 0, s[98:99]
	global_load_dwordx4 v[184:187], v[216:217], off
	global_load_dwordx4 v[188:191], v[216:217], off offset:256
	s_mov_b32 s98, 0x48000
	v_lshl_add_u64 v[216:217], v[144:145], 0, s[98:99]
	global_load_dwordx4 v[192:195], v[216:217], off
	global_load_dwordx4 v[196:199], v[216:217], off offset:256
	s_mov_b32 s98, 0x50000
	v_lshl_add_u64 v[216:217], v[144:145], 0, s[98:99]
	global_load_dwordx4 v[200:203], v[216:217], off
	global_load_dwordx4 v[204:207], v[216:217], off offset:256
	s_mov_b32 s98, 0x58000
	v_lshl_add_u64 v[216:217], v[144:145], 0, s[98:99]
	global_load_dwordx4 v[208:211], v[216:217], off
	global_load_dwordx4 v[212:215], v[216:217], off offset:256
	s_waitcnt vmcnt(15)
	v_mov_b32_e32 v132, v152
	v_mov_b32_e32 v133, v153
	v_mov_b32_e32 v134, v154
	v_mov_b32_e32 v135, v155
	v_lshl_add_u32 v131, v142, 2, s7
	ds_read_b32 v146, v131 offset:1024
	v_readlane_b32 s8, v252, 11
	v_readlane_b32 s9, v252, 12
	s_andn2_b64 vcc, exec, s[8:9]
	s_nop 0
	v_lshlrev_b32_e32 v148, 16, v132
	v_and_b32_e32 v149, 0xffff0000, v132
	v_lshlrev_b32_e32 v132, 16, v133
	v_and_b32_e32 v133, 0xffff0000, v133
	v_lshlrev_b32_e32 v150, 16, v134
	v_and_b32_e32 v151, 0xffff0000, v134
	v_lshlrev_b32_e32 v134, 16, v135
	v_and_b32_e32 v135, 0xffff0000, v135
	s_waitcnt lgkmcnt(0)
	v_pk_fma_f32 v[126:127], v[126:127], v[146:147], v[132:133] op_sel_hi:[1,0,1]
	v_pk_fma_f32 v[124:125], v[124:125], v[146:147], v[148:149] op_sel_hi:[1,0,1]
	v_pk_fma_f32 v[132:133], v[122:123], v[146:147], v[134:135] op_sel_hi:[1,0,1]
	v_pk_fma_f32 v[122:123], v[120:121], v[146:147], v[150:151] op_sel_hi:[1,0,1]
	v_cvt_pk_bf16_f32 v120, v124, v125
	v_cvt_pk_bf16_f32 v121, v126, v127
	v_or_b32_e32 v134, 16, v142
	v_cvt_pk_bf16_f32 v122, v122, v123
	v_cvt_pk_bf16_f32 v123, v132, v133
	s_waitcnt vmcnt(14)
	v_mov_b32_e32 v124, v156
	v_mov_b32_e32 v125, v157
	v_mov_b32_e32 v126, v158
	v_mov_b32_e32 v127, v159
	v_add_u32_e32 v132, s6, v134
	v_ashrrev_i32_e32 v133, 31, v132
	v_lshlrev_b64 v[132:133], 11, v[132:133]
	v_lshl_add_u64 v[132:133], s[24:25], 0, v[132:133]
	global_store_dwordx4 v[144:145], v[120:123], off
	v_lshl_add_u64 v[132:133], v[132:133], 0, v[128:129]
	s_nop 0
	v_lshlrev_b32_e32 v120, 16, v124
	v_and_b32_e32 v121, 0xffff0000, v124
	v_lshlrev_b32_e32 v122, 16, v125
	v_and_b32_e32 v123, 0xffff0000, v125
	v_lshlrev_b32_e32 v124, 16, v126
	v_and_b32_e32 v125, 0xffff0000, v126
	v_lshlrev_b32_e32 v126, 16, v127
	v_and_b32_e32 v127, 0xffff0000, v127
	v_pk_fma_f32 v[114:115], v[114:115], v[146:147], v[122:123] op_sel_hi:[1,0,1]
	v_pk_fma_f32 v[112:113], v[112:113], v[146:147], v[120:121] op_sel_hi:[1,0,1]
	v_pk_fma_f32 v[118:119], v[118:119], v[146:147], v[126:127] op_sel_hi:[1,0,1]
	v_pk_fma_f32 v[116:117], v[116:117], v[146:147], v[124:125] op_sel_hi:[1,0,1]
	v_cvt_pk_bf16_f32 v112, v112, v113
	v_cvt_pk_bf16_f32 v113, v114, v115
	v_lshl_add_u32 v120, v134, 2, s7
	v_cvt_pk_bf16_f32 v114, v116, v117
	v_cvt_pk_bf16_f32 v115, v118, v119
	s_waitcnt vmcnt(14)
	v_mov_b32_e32 v116, v160
	v_mov_b32_e32 v117, v161
	v_mov_b32_e32 v118, v162
	v_mov_b32_e32 v119, v163
	ds_read_b32 v120, v120 offset:1024
	global_store_dwordx4 v[144:145], v[112:115], off offset:256
	s_nop 0
	s_nop 0
	v_lshlrev_b32_e32 v112, 16, v116
	v_and_b32_e32 v113, 0xffff0000, v116
	v_lshlrev_b32_e32 v114, 16, v117
	v_and_b32_e32 v115, 0xffff0000, v117
	v_lshlrev_b32_e32 v116, 16, v118
	v_and_b32_e32 v117, 0xffff0000, v118
	v_lshlrev_b32_e32 v118, 16, v119
	v_and_b32_e32 v119, 0xffff0000, v119
	s_waitcnt lgkmcnt(0)
	v_pk_fma_f32 v[110:111], v[110:111], v[120:121], v[114:115] op_sel_hi:[1,0,1]
	v_pk_fma_f32 v[108:109], v[108:109], v[120:121], v[112:113] op_sel_hi:[1,0,1]
	v_pk_fma_f32 v[112:113], v[106:107], v[120:121], v[118:119] op_sel_hi:[1,0,1]
	v_pk_fma_f32 v[106:107], v[104:105], v[120:121], v[116:117] op_sel_hi:[1,0,1]
	v_cvt_pk_bf16_f32 v104, v108, v109
	v_cvt_pk_bf16_f32 v105, v110, v111
	v_or_b32_e32 v114, 32, v142
	v_cvt_pk_bf16_f32 v106, v106, v107
	v_cvt_pk_bf16_f32 v107, v112, v113
	s_waitcnt vmcnt(14)
; __device__ __forceinline__ unsigned cvt_pk_bf16(float lo, float hi) { unsigned r; asm volatile("v_cvt_pk_bf16_f32 %0, %1, %2" : "=v"(r) : "v"(lo), "v"(hi)); return r; }
;     __device__ __forceinline__ void operator()(const f32x4 (&acc)[2][2][4][2], const Unit& u, int wr, int wc, int fr, int fq) const {
;         const int col0 = u.pn * BM + wc * 32 + 8 * fq;
; #pragma unroll
;         for (int ai = 0; ai < 2; ++ai)
; #pragma unroll
;             for (int m = 0; m < 4; ++m) { const int rt = ai * HALF + wr * 64 + m * 16 + fr; const float r = tab[256 + rt]; const size_t off = (size_t)(u.pm * BM + rt) * 1024 + col0;
; #pragma unroll
;                 for (int bj = 0; bj < 2; ++bj) {
;                     const u32x4 xw = *(const u32x4*)(x1b + off + bj * HALF);
;                     f32x4 x0, x1;
;                     x0[0] = __uint_as_float(xw.x << 16); x0[1] = __uint_as_float(xw.x & 0xffff0000u); x0[2] = __uint_as_float(xw.y << 16); x0[3] = __uint_as_float(xw.y & 0xffff0000u);
;                     x1[0] = __uint_as_float(xw.z << 16); x1[1] = __uint_as_float(xw.z & 0xffff0000u); x1[2] = __uint_as_float(xw.w << 16); x1[3] = __uint_as_float(xw.w & 0xffff0000u);
;                     const f32x4 v0 = x0 + acc[ai][bj][m][0] * r, v1 = x1 + acc[ai][bj][m][1] * r;
;                     u32x4 w; w.x = cvt_pk_bf16(v0[0], v0[1]); w.y = cvt_pk_bf16(v0[2], v0[3]); w.z = cvt_pk_bf16(v1[0], v1[1]); w.w = cvt_pk_bf16(v1[2], v1[3]);
;                     *(u32x4*)(x1b + off + bj * HALF) = w; } }
;     }
	v_mov_b32_e32 v108, v164
	v_mov_b32_e32 v109, v165
	v_mov_b32_e32 v110, v166
	v_mov_b32_e32 v111, v167
	v_add_u32_e32 v112, s6, v114
	v_ashrrev_i32_e32 v113, 31, v112
	v_lshlrev_b64 v[112:113], 11, v[112:113]
	v_lshl_add_u64 v[112:113], s[24:25], 0, v[112:113]
	global_store_dwordx4 v[132:133], v[104:107], off
	v_lshl_add_u64 v[112:113], v[112:113], 0, v[128:129]
	s_nop 0
	v_lshlrev_b32_e32 v104, 16, v108
	v_and_b32_e32 v105, 0xffff0000, v108
	v_lshlrev_b32_e32 v106, 16, v109
	v_and_b32_e32 v107, 0xffff0000, v109
	v_lshlrev_b32_e32 v108, 16, v110
	v_and_b32_e32 v109, 0xffff0000, v110
	v_lshlrev_b32_e32 v110, 16, v111
	v_and_b32_e32 v111, 0xffff0000, v111
	v_pk_fma_f32 v[98:99], v[98:99], v[120:121], v[106:107] op_sel_hi:[1,0,1]
	v_pk_fma_f32 v[96:97], v[96:97], v[120:121], v[104:105] op_sel_hi:[1,0,1]
	v_pk_fma_f32 v[102:103], v[102:103], v[120:121], v[110:111] op_sel_hi:[1,0,1]
	v_pk_fma_f32 v[100:101], v[100:101], v[120:121], v[108:109] op_sel_hi:[1,0,1]
	v_cvt_pk_bf16_f32 v96, v96, v97
	v_cvt_pk_bf16_f32 v97, v98, v99
	v_lshl_add_u32 v104, v114, 2, s7
	v_cvt_pk_bf16_f32 v98, v100, v101
	v_cvt_pk_bf16_f32 v99, v102, v103
	s_waitcnt vmcnt(14)
	v_mov_b32_e32 v100, v168
	v_mov_b32_e32 v101, v169
	v_mov_b32_e32 v102, v170
	v_mov_b32_e32 v103, v171
	ds_read_b32 v104, v104 offset:1024
	global_store_dwordx4 v[132:133], v[96:99], off offset:256
	s_nop 0
	s_nop 0
	v_lshlrev_b32_e32 v96, 16, v100
	v_and_b32_e32 v97, 0xffff0000, v100
	v_lshlrev_b32_e32 v98, 16, v101
	v_and_b32_e32 v99, 0xffff0000, v101
	v_lshlrev_b32_e32 v100, 16, v102
	v_and_b32_e32 v101, 0xffff0000, v102
	v_lshlrev_b32_e32 v102, 16, v103
	v_and_b32_e32 v103, 0xffff0000, v103
	s_waitcnt lgkmcnt(0)
	v_pk_fma_f32 v[94:95], v[94:95], v[104:105], v[98:99] op_sel_hi:[1,0,1]
	v_pk_fma_f32 v[92:93], v[92:93], v[104:105], v[96:97] op_sel_hi:[1,0,1]
	v_pk_fma_f32 v[96:97], v[90:91], v[104:105], v[102:103] op_sel_hi:[1,0,1]
	v_pk_fma_f32 v[90:91], v[88:89], v[104:105], v[100:101] op_sel_hi:[1,0,1]
	v_cvt_pk_bf16_f32 v88, v92, v93
	v_cvt_pk_bf16_f32 v89, v94, v95
	v_or_b32_e32 v98, 48, v142
	v_cvt_pk_bf16_f32 v90, v90, v91
	v_cvt_pk_bf16_f32 v91, v96, v97
	s_waitcnt vmcnt(14)
	v_mov_b32_e32 v92, v172
	v_mov_b32_e32 v93, v173
	v_mov_b32_e32 v94, v174
	v_mov_b32_e32 v95, v175
	v_add_u32_e32 v96, s6, v98
	v_ashrrev_i32_e32 v97, 31, v96
	v_lshlrev_b64 v[96:97], 11, v[96:97]
	v_lshl_add_u64 v[96:97], s[24:25], 0, v[96:97]
	global_store_dwordx4 v[112:113], v[88:91], off
	v_lshl_add_u64 v[96:97], v[96:97], 0, v[128:129]
	s_nop 0
	v_lshlrev_b32_e32 v88, 16, v92
	v_and_b32_e32 v89, 0xffff0000, v92
	v_lshlrev_b32_e32 v90, 16, v93
	v_and_b32_e32 v91, 0xffff0000, v93
	v_lshlrev_b32_e32 v92, 16, v94
	v_and_b32_e32 v93, 0xffff0000, v94
	v_lshlrev_b32_e32 v94, 16, v95
	v_and_b32_e32 v95, 0xffff0000, v95
	v_pk_fma_f32 v[82:83], v[82:83], v[104:105], v[90:91] op_sel_hi:[1,0,1]
	v_pk_fma_f32 v[80:81], v[80:81], v[104:105], v[88:89] op_sel_hi:[1,0,1]
	v_pk_fma_f32 v[86:87], v[86:87], v[104:105], v[94:95] op_sel_hi:[1,0,1]
	v_pk_fma_f32 v[84:85], v[84:85], v[104:105], v[92:93] op_sel_hi:[1,0,1]
	v_cvt_pk_bf16_f32 v80, v80, v81
	v_cvt_pk_bf16_f32 v81, v82, v83
	v_lshl_add_u32 v88, v98, 2, s7
	v_cvt_pk_bf16_f32 v82, v84, v85
	v_cvt_pk_bf16_f32 v83, v86, v87
	s_waitcnt vmcnt(14)
	v_mov_b32_e32 v84, v176
	v_mov_b32_e32 v85, v177
	v_mov_b32_e32 v86, v178
	v_mov_b32_e32 v87, v179
	ds_read_b32 v88, v88 offset:1024
	global_store_dwordx4 v[112:113], v[80:83], off offset:256
	s_nop 0
	s_nop 0
	v_lshlrev_b32_e32 v80, 16, v84
	v_and_b32_e32 v81, 0xffff0000, v84
	v_lshlrev_b32_e32 v82, 16, v85
	v_and_b32_e32 v83, 0xffff0000, v85
	v_lshlrev_b32_e32 v84, 16, v86
	v_and_b32_e32 v85, 0xffff0000, v86
	v_lshlrev_b32_e32 v86, 16, v87
	v_and_b32_e32 v87, 0xffff0000, v87
	s_waitcnt lgkmcnt(0)
	v_pk_fma_f32 v[78:79], v[78:79], v[88:89], v[82:83] op_sel_hi:[1,0,1]
	v_pk_fma_f32 v[76:77], v[76:77], v[88:89], v[80:81] op_sel_hi:[1,0,1]
	v_pk_fma_f32 v[80:81], v[74:75], v[88:89], v[86:87] op_sel_hi:[1,0,1]
	v_pk_fma_f32 v[74:75], v[72:73], v[88:89], v[84:85] op_sel_hi:[1,0,1]
	v_cvt_pk_bf16_f32 v72, v76, v77
	v_cvt_pk_bf16_f32 v73, v78, v79
	s_nop 0
	v_cvt_pk_bf16_f32 v74, v74, v75
	v_cvt_pk_bf16_f32 v75, v80, v81
	s_waitcnt vmcnt(14)
	v_mov_b32_e32 v76, v180
	v_mov_b32_e32 v77, v181
	v_mov_b32_e32 v78, v182
	v_mov_b32_e32 v79, v183
	v_add_u32_e32 v80, 0x80, v130
	v_ashrrev_i32_e32 v81, 31, v80
	v_lshlrev_b64 v[80:81], 11, v[80:81]
	v_lshl_add_u64 v[80:81], s[24:25], 0, v[80:81]
	global_store_dwordx4 v[96:97], v[72:75], off
	v_lshl_add_u64 v[80:81], v[80:81], 0, v[128:129]
	s_nop 0
	v_lshlrev_b32_e32 v72, 16, v76
	v_and_b32_e32 v73, 0xffff0000, v76
	v_lshlrev_b32_e32 v74, 16, v77
	v_and_b32_e32 v75, 0xffff0000, v77
	v_lshlrev_b32_e32 v76, 16, v78
	v_and_b32_e32 v77, 0xffff0000, v78
	v_lshlrev_b32_e32 v78, 16, v79
	v_and_b32_e32 v79, 0xffff0000, v79
	v_pk_fma_f32 v[58:59], v[58:59], v[88:89], v[74:75] op_sel_hi:[1,0,1]
	v_pk_fma_f32 v[56:57], v[56:57], v[88:89], v[72:73] op_sel_hi:[1,0,1]
	v_pk_fma_f32 v[62:63], v[62:63], v[88:89], v[78:79] op_sel_hi:[1,0,1]
	v_pk_fma_f32 v[60:61], v[60:61], v[88:89], v[76:77] op_sel_hi:[1,0,1]
	v_cvt_pk_bf16_f32 v56, v56, v57
	v_cvt_pk_bf16_f32 v57, v58, v59
	s_nop 0
	v_cvt_pk_bf16_f32 v58, v60, v61
	v_cvt_pk_bf16_f32 v59, v62, v63
	s_waitcnt vmcnt(14)
	v_mov_b32_e32 v60, v184
	v_mov_b32_e32 v61, v185
	v_mov_b32_e32 v62, v186
	v_mov_b32_e32 v63, v187
	ds_read_b32 v72, v131 offset:1536
	global_store_dwordx4 v[96:97], v[56:59], off offset:256
	s_nop 0
	s_nop 0
	v_lshlrev_b32_e32 v56, 16, v60
	v_and_b32_e32 v57, 0xffff0000, v60
	v_lshlrev_b32_e32 v58, 16, v61
	v_and_b32_e32 v59, 0xffff0000, v61
	v_lshlrev_b32_e32 v60, 16, v62
	v_and_b32_e32 v61, 0xffff0000, v62
	v_lshlrev_b32_e32 v62, 16, v63
	v_and_b32_e32 v63, 0xffff0000, v63
	s_waitcnt lgkmcnt(0)
; __device__ __forceinline__ unsigned cvt_pk_bf16(float lo, float hi) { unsigned r; asm volatile("v_cvt_pk_bf16_f32 %0, %1, %2" : "=v"(r) : "v"(lo), "v"(hi)); return r; }
;     __device__ __forceinline__ void operator()(const f32x4 (&acc)[2][2][4][2], const Unit& u, int wr, int wc, int fr, int fq) const {
;         const int col0 = u.pn * BM + wc * 32 + 8 * fq;
; #pragma unroll
;         for (int ai = 0; ai < 2; ++ai)
; #pragma unroll
;             for (int m = 0; m < 4; ++m) { const int rt = ai * HALF + wr * 64 + m * 16 + fr; const float r = tab[256 + rt]; const size_t off = (size_t)(u.pm * BM + rt) * 1024 + col0;
; #pragma unroll
;                 for (int bj = 0; bj < 2; ++bj) {
;                     const u32x4 xw = *(const u32x4*)(x1b + off + bj * HALF);
;                     f32x4 x0, x1;
;                     x0[0] = __uint_as_float(xw.x << 16); x0[1] = __uint_as_float(xw.x & 0xffff0000u); x0[2] = __uint_as_float(xw.y << 16); x0[3] = __uint_as_float(xw.y & 0xffff0000u);
;                     x1[0] = __uint_as_float(xw.z << 16); x1[1] = __uint_as_float(xw.z & 0xffff0000u); x1[2] = __uint_as_float(xw.w << 16); x1[3] = __uint_as_float(xw.w & 0xffff0000u);
;                     const f32x4 v0 = x0 + acc[ai][bj][m][0] * r, v1 = x1 + acc[ai][bj][m][1] * r;
;                     u32x4 w; w.x = cvt_pk_bf16(v0[0], v0[1]); w.y = cvt_pk_bf16(v0[2], v0[3]); w.z = cvt_pk_bf16(v1[0], v1[1]); w.w = cvt_pk_bf16(v1[2], v1[3]);
;                     *(u32x4*)(x1b + off + bj * HALF) = w; } }
;     }
	v_pk_fma_f32 v[58:59], v[70:71], v[72:73], v[58:59] op_sel_hi:[1,0,1]
	v_pk_fma_f32 v[56:57], v[68:69], v[72:73], v[56:57] op_sel_hi:[1,0,1]
	v_pk_fma_f32 v[62:63], v[66:67], v[72:73], v[62:63] op_sel_hi:[1,0,1]
	v_pk_fma_f32 v[60:61], v[64:65], v[72:73], v[60:61] op_sel_hi:[1,0,1]
	v_cvt_pk_bf16_f32 v56, v56, v57
	v_cvt_pk_bf16_f32 v57, v58, v59
	v_add_u32_e32 v64, 0x90, v130
	v_cvt_pk_bf16_f32 v58, v60, v61
	v_cvt_pk_bf16_f32 v59, v62, v63
	s_waitcnt vmcnt(14)
	v_mov_b32_e32 v60, v188
	v_mov_b32_e32 v61, v189
	v_mov_b32_e32 v62, v190
	v_mov_b32_e32 v63, v191
	v_ashrrev_i32_e32 v65, 31, v64
	v_lshlrev_b64 v[64:65], 11, v[64:65]
	v_lshl_add_u64 v[64:65], s[24:25], 0, v[64:65]
	global_store_dwordx4 v[80:81], v[56:59], off
	v_lshl_add_u64 v[64:65], v[64:65], 0, v[128:129]
	s_nop 0
	v_lshlrev_b32_e32 v56, 16, v60
	v_and_b32_e32 v57, 0xffff0000, v60
	v_lshlrev_b32_e32 v58, 16, v61
	v_and_b32_e32 v59, 0xffff0000, v61
	v_lshlrev_b32_e32 v60, 16, v62
	v_and_b32_e32 v61, 0xffff0000, v62
	v_lshlrev_b32_e32 v62, 16, v63
	v_and_b32_e32 v63, 0xffff0000, v63
	v_pk_fma_f32 v[50:51], v[50:51], v[72:73], v[58:59] op_sel_hi:[1,0,1]
	v_pk_fma_f32 v[48:49], v[48:49], v[72:73], v[56:57] op_sel_hi:[1,0,1]
	v_pk_fma_f32 v[54:55], v[54:55], v[72:73], v[62:63] op_sel_hi:[1,0,1]
	v_pk_fma_f32 v[52:53], v[52:53], v[72:73], v[60:61] op_sel_hi:[1,0,1]
	v_cvt_pk_bf16_f32 v48, v48, v49
	v_cvt_pk_bf16_f32 v49, v50, v51
	s_nop 0
	v_cvt_pk_bf16_f32 v50, v52, v53
	v_cvt_pk_bf16_f32 v51, v54, v55
	s_waitcnt vmcnt(14)
	v_mov_b32_e32 v52, v192
	v_mov_b32_e32 v53, v193
	v_mov_b32_e32 v54, v194
	v_mov_b32_e32 v55, v195
	ds_read_b32 v56, v131 offset:1600
	global_store_dwordx4 v[80:81], v[48:51], off offset:256
	s_nop 0
	s_nop 0
	v_lshlrev_b32_e32 v48, 16, v52
	v_and_b32_e32 v49, 0xffff0000, v52
	v_lshlrev_b32_e32 v50, 16, v53
	v_and_b32_e32 v51, 0xffff0000, v53
	v_lshlrev_b32_e32 v52, 16, v54
	v_and_b32_e32 v53, 0xffff0000, v54
	v_lshlrev_b32_e32 v54, 16, v55
	v_and_b32_e32 v55, 0xffff0000, v55
	s_waitcnt lgkmcnt(0)
	v_pk_fma_f32 v[46:47], v[46:47], v[56:57], v[50:51] op_sel_hi:[1,0,1]
	v_pk_fma_f32 v[44:45], v[44:45], v[56:57], v[48:49] op_sel_hi:[1,0,1]
	v_pk_fma_f32 v[48:49], v[42:43], v[56:57], v[54:55] op_sel_hi:[1,0,1]
	v_pk_fma_f32 v[42:43], v[40:41], v[56:57], v[52:53] op_sel_hi:[1,0,1]
	v_cvt_pk_bf16_f32 v40, v44, v45
	v_cvt_pk_bf16_f32 v41, v46, v47
	s_nop 0
	v_cvt_pk_bf16_f32 v42, v42, v43
	v_cvt_pk_bf16_f32 v43, v48, v49
	s_waitcnt vmcnt(14)
	v_mov_b32_e32 v44, v196
	v_mov_b32_e32 v45, v197
	v_mov_b32_e32 v46, v198
	v_mov_b32_e32 v47, v199
	v_add_u32_e32 v48, 0xa0, v130
	v_ashrrev_i32_e32 v49, 31, v48
	v_lshlrev_b64 v[48:49], 11, v[48:49]
	v_lshl_add_u64 v[48:49], s[24:25], 0, v[48:49]
	global_store_dwordx4 v[64:65], v[40:43], off
	v_lshl_add_u64 v[48:49], v[48:49], 0, v[128:129]
	s_nop 0
	v_lshlrev_b32_e32 v40, 16, v44
	v_and_b32_e32 v41, 0xffff0000, v44
	v_lshlrev_b32_e32 v42, 16, v45
	v_and_b32_e32 v43, 0xffff0000, v45
	v_lshlrev_b32_e32 v44, 16, v46
	v_and_b32_e32 v45, 0xffff0000, v46
	v_lshlrev_b32_e32 v46, 16, v47
	v_and_b32_e32 v47, 0xffff0000, v47
	v_pk_fma_f32 v[34:35], v[34:35], v[56:57], v[42:43] op_sel_hi:[1,0,1]
	v_pk_fma_f32 v[32:33], v[32:33], v[56:57], v[40:41] op_sel_hi:[1,0,1]
	v_pk_fma_f32 v[38:39], v[38:39], v[56:57], v[46:47] op_sel_hi:[1,0,1]
	v_pk_fma_f32 v[36:37], v[36:37], v[56:57], v[44:45] op_sel_hi:[1,0,1]
	v_cvt_pk_bf16_f32 v32, v32, v33
	v_cvt_pk_bf16_f32 v33, v34, v35
	s_nop 0
	v_cvt_pk_bf16_f32 v34, v36, v37
	v_cvt_pk_bf16_f32 v35, v38, v39
	s_waitcnt vmcnt(14)
	v_mov_b32_e32 v36, v200
	v_mov_b32_e32 v37, v201
	v_mov_b32_e32 v38, v202
	v_mov_b32_e32 v39, v203
	ds_read_b32 v40, v131 offset:1664
	global_store_dwordx4 v[64:65], v[32:35], off offset:256
	s_nop 0
	s_nop 0
	v_lshlrev_b32_e32 v32, 16, v36
	v_and_b32_e32 v33, 0xffff0000, v36
	v_lshlrev_b32_e32 v34, 16, v37
	v_and_b32_e32 v35, 0xffff0000, v37
	v_lshlrev_b32_e32 v36, 16, v38
	v_and_b32_e32 v37, 0xffff0000, v38
	v_lshlrev_b32_e32 v38, 16, v39
	v_and_b32_e32 v39, 0xffff0000, v39
	s_waitcnt lgkmcnt(0)
; __device__ __forceinline__ unsigned cvt_pk_bf16(float lo, float hi) { unsigned r; asm volatile("v_cvt_pk_bf16_f32 %0, %1, %2" : "=v"(r) : "v"(lo), "v"(hi)); return r; }
; #define PG8_WAIT_V(n) asm volatile("s_waitcnt vmcnt(" #n ")" ::: "memory")
; #define PG8_BAR __builtin_amdgcn_s_barrier()
;     __device__ __forceinline__ void operator()(const f32x4 (&acc)[2][2][4][2], const Unit& u, int wr, int wc, int fr, int fq) const {
;         const int col0 = u.pn * BM + wc * 32 + 8 * fq;
; #pragma unroll
;         for (int ai = 0; ai < 2; ++ai)
; #pragma unroll
;             for (int m = 0; m < 4; ++m) { const int rt = ai * HALF + wr * 64 + m * 16 + fr; const float r = tab[256 + rt]; const size_t off = (size_t)(u.pm * BM + rt) * 1024 + col0;
; #pragma unroll
;                 for (int bj = 0; bj < 2; ++bj) {
;                     const u32x4 xw = *(const u32x4*)(x1b + off + bj * HALF);
;                     f32x4 x0, x1;
;                     x0[0] = __uint_as_float(xw.x << 16); x0[1] = __uint_as_float(xw.x & 0xffff0000u); x0[2] = __uint_as_float(xw.y << 16); x0[3] = __uint_as_float(xw.y & 0xffff0000u);
;                     x1[0] = __uint_as_float(xw.z << 16); x1[1] = __uint_as_float(xw.z & 0xffff0000u); x1[2] = __uint_as_float(xw.w << 16); x1[3] = __uint_as_float(xw.w & 0xffff0000u);
;                     const f32x4 v0 = x0 + acc[ai][bj][m][0] * r, v1 = x1 + acc[ai][bj][m][1] * r;
;                     u32x4 w; w.x = cvt_pk_bf16(v0[0], v0[1]); w.y = cvt_pk_bf16(v0[2], v0[3]); w.z = cvt_pk_bf16(v1[0], v1[1]); w.w = cvt_pk_bf16(v1[2], v1[3]);
;                     *(u32x4*)(x1b + off + bj * HALF) = w; } }
;     }
; template <int ROT, class Epi0, class Epi1, class Late, class Post0>
; __device__ __forceinline__ void gemm_phase_pair(PG8_LAS unsigned char* lds, const Gemm g0, const Gemm g1, const Unit u, const Epi0& E0, const Epi1& E1, int wid_in, const Late& late, const Post0& post0) {
;     ...
;     E0(acc, u, wr, wc, fr, fq);
;     PG8_WAIT_V(0); PG8_BAR; post0();
	v_pk_fma_f32 v[30:31], v[30:31], v[40:41], v[34:35] op_sel_hi:[1,0,1]
	v_pk_fma_f32 v[28:29], v[28:29], v[40:41], v[32:33] op_sel_hi:[1,0,1]
	v_pk_fma_f32 v[32:33], v[26:27], v[40:41], v[38:39] op_sel_hi:[1,0,1]
	v_pk_fma_f32 v[26:27], v[24:25], v[40:41], v[36:37] op_sel_hi:[1,0,1]
	v_cvt_pk_bf16_f32 v24, v28, v29
	v_cvt_pk_bf16_f32 v25, v30, v31
	s_nop 0
	v_cvt_pk_bf16_f32 v26, v26, v27
	v_cvt_pk_bf16_f32 v27, v32, v33
	s_waitcnt vmcnt(14)
	v_mov_b32_e32 v28, v204
	v_mov_b32_e32 v29, v205
	v_mov_b32_e32 v30, v206
	v_mov_b32_e32 v31, v207
	v_add_u32_e32 v32, 0xb0, v130
	v_ashrrev_i32_e32 v33, 31, v32
	v_lshlrev_b64 v[32:33], 11, v[32:33]
	v_lshl_add_u64 v[32:33], s[24:25], 0, v[32:33]
	global_store_dwordx4 v[48:49], v[24:27], off
	v_lshl_add_u64 v[32:33], v[32:33], 0, v[128:129]
	s_nop 0
	v_lshlrev_b32_e32 v24, 16, v28
	v_and_b32_e32 v25, 0xffff0000, v28
	v_lshlrev_b32_e32 v26, 16, v29
	v_and_b32_e32 v27, 0xffff0000, v29
	v_lshlrev_b32_e32 v28, 16, v30
	v_and_b32_e32 v29, 0xffff0000, v30
	v_lshlrev_b32_e32 v30, 16, v31
	v_and_b32_e32 v31, 0xffff0000, v31
	v_pk_fma_f32 v[18:19], v[18:19], v[40:41], v[26:27] op_sel_hi:[1,0,1]
	v_pk_fma_f32 v[16:17], v[16:17], v[40:41], v[24:25] op_sel_hi:[1,0,1]
	v_pk_fma_f32 v[22:23], v[22:23], v[40:41], v[30:31] op_sel_hi:[1,0,1]
	v_pk_fma_f32 v[20:21], v[20:21], v[40:41], v[28:29] op_sel_hi:[1,0,1]
	v_cvt_pk_bf16_f32 v16, v16, v17
	v_cvt_pk_bf16_f32 v17, v18, v19
	s_nop 0
	v_cvt_pk_bf16_f32 v18, v20, v21
	v_cvt_pk_bf16_f32 v19, v22, v23
	s_waitcnt vmcnt(14)
	v_mov_b32_e32 v20, v208
	v_mov_b32_e32 v21, v209
	v_mov_b32_e32 v22, v210
	v_mov_b32_e32 v23, v211
	ds_read_b32 v24, v131 offset:1728
	global_store_dwordx4 v[48:49], v[16:19], off offset:256
	s_nop 0
	s_nop 0
	v_lshlrev_b32_e32 v16, 16, v20
	v_and_b32_e32 v17, 0xffff0000, v20
	v_lshlrev_b32_e32 v18, 16, v21
	v_and_b32_e32 v19, 0xffff0000, v21
	v_lshlrev_b32_e32 v20, 16, v22
	v_and_b32_e32 v21, 0xffff0000, v22
	v_lshlrev_b32_e32 v22, 16, v23
	v_and_b32_e32 v23, 0xffff0000, v23
	s_waitcnt lgkmcnt(0)
	v_pk_fma_f32 v[14:15], v[14:15], v[24:25], v[18:19] op_sel_hi:[1,0,1]
	v_pk_fma_f32 v[12:13], v[12:13], v[24:25], v[16:17] op_sel_hi:[1,0,1]
	v_pk_fma_f32 v[16:17], v[10:11], v[24:25], v[22:23] op_sel_hi:[1,0,1]
	v_pk_fma_f32 v[10:11], v[8:9], v[24:25], v[20:21] op_sel_hi:[1,0,1]
	v_cvt_pk_bf16_f32 v8, v12, v13
	v_cvt_pk_bf16_f32 v9, v14, v15
	s_nop 0
	v_cvt_pk_bf16_f32 v10, v10, v11
	v_cvt_pk_bf16_f32 v11, v16, v17
	s_waitcnt vmcnt(14)
	v_mov_b32_e32 v12, v212
	v_mov_b32_e32 v13, v213
	v_mov_b32_e32 v14, v214
	v_mov_b32_e32 v15, v215
	s_nop 0
	global_store_dwordx4 v[32:33], v[8:11], off
	s_nop 0
	s_nop 0
	v_lshlrev_b32_e32 v8, 16, v12
	v_and_b32_e32 v9, 0xffff0000, v12
	v_lshlrev_b32_e32 v10, 16, v13
	v_and_b32_e32 v11, 0xffff0000, v13
	v_lshlrev_b32_e32 v12, 16, v14
	v_and_b32_e32 v13, 0xffff0000, v14
	v_lshlrev_b32_e32 v14, 16, v15
	v_and_b32_e32 v15, 0xffff0000, v15
	v_pk_fma_f32 v[4:5], v[4:5], v[24:25], v[8:9] op_sel_hi:[1,0,1]
	v_pk_fma_f32 v[8:9], v[2:3], v[24:25], v[14:15] op_sel_hi:[1,0,1]
	v_pk_fma_f32 v[2:3], v[0:1], v[24:25], v[12:13] op_sel_hi:[1,0,1]
	v_pk_fma_f32 v[6:7], v[6:7], v[24:25], v[10:11] op_sel_hi:[1,0,1]
	v_cvt_pk_bf16_f32 v0, v4, v5
	s_nop 0
	v_cvt_pk_bf16_f32 v1, v6, v7
	v_cvt_pk_bf16_f32 v2, v2, v3
	v_cvt_pk_bf16_f32 v3, v8, v9
	global_store_dwordx4 v[32:33], v[0:3], off offset:256
	s_waitcnt vmcnt(0)
	s_barrier
	s_cbranch_vccnz .LBB0_884
	v_mbcnt_lo_u32_b32 v0, -1, 0
	v_mbcnt_hi_u32_b32 v0, -1, v0
	s_nop 0
	v_cmp_eq_u32_e32 vcc, 0, v0
	s_and_saveexec_b64 s[8:9], vcc
	s_cbranch_execz .LBB0_883
	s_mov_b64 s[24:25], exec
	v_mbcnt_lo_u32_b32 v0, s24, 0
	v_mbcnt_hi_u32_b32 v0, s25, v0
	v_cmp_eq_u32_e32 vcc, 0, v0
	s_and_b64 s[26:27], exec, vcc
	s_mov_b64 exec, s[26:27]
	s_cbranch_execz .LBB0_883
	s_bcnt1_i32_b64 s7, s[24:25]
	v_mov_b32_e32 v0, 0
	v_mov_b32_e32 v1, s7
	global_atomic_add v0, v1, s[10:11]

; __global__ void __launch_bounds__(NWAVES * 64, 2) mk_fwd(Args args) {
	.amdhsa_kernel _Z6mk_fwd4Args
		.amdhsa_group_segment_fixed_size 0
		.amdhsa_private_segment_fixed_size 0
		.amdhsa_kernarg_size 440
		.amdhsa_user_sgpr_count 2
		.amdhsa_user_sgpr_dispatch_ptr 0
		.amdhsa_user_sgpr_queue_ptr 0
		.amdhsa_user_sgpr_kernarg_segment_ptr 1
		.amdhsa_user_sgpr_dispatch_id 0
		.amdhsa_user_sgpr_kernarg_preload_length 0
		.amdhsa_user_sgpr_kernarg_preload_offset 0
		.amdhsa_user_sgpr_private_segment_size 0
		.amdhsa_uses_dynamic_stack 0
		.amdhsa_enable_private_segment 0
		.amdhsa_system_sgpr_workgroup_id_x 1
		.amdhsa_system_sgpr_workgroup_id_y 0
		.amdhsa_system_sgpr_workgroup_id_z 0
		.amdhsa_system_sgpr_workgroup_info 0
		.amdhsa_system_vgpr_workitem_id 0
		.amdhsa_next_free_vgpr 253
		.amdhsa_next_free_sgpr 100
		.amdhsa_accum_offset 256
		.amdhsa_reserve_vcc 1
		.amdhsa_float_round_mode_32 0
		.amdhsa_float_round_mode_16_64 0
		.amdhsa_float_denorm_mode_32 3
		.amdhsa_float_denorm_mode_16_64 3
		.amdhsa_dx10_clamp 1
		.amdhsa_ieee_mode 1
		.amdhsa_fp16_overflow 0
		.amdhsa_tg_split 0
		.amdhsa_exception_fp_ieee_invalid_op 0
		.amdhsa_exception_fp_denorm_src 0
		.amdhsa_exception_fp_ieee_div_zero 0
		.amdhsa_exception_fp_ieee_overflow 0
		.amdhsa_exception_fp_ieee_underflow 0
		.amdhsa_exception_fp_ieee_inexact 0
		.amdhsa_exception_int_div_zero 0
	.end_amdhsa_kernel

; __global__ void __launch_bounds__(NWAVES * 64, 2) mk_fwd(Args args) {
.Lfunc_end0:
	.size	_Z6mk_fwd4Args, .Lfunc_end0-_Z6mk_fwd4Args
	.set _Z6mk_fwd4Args.num_vgpr, 253
	.set _Z6mk_fwd4Args.num_agpr, 0
	.set _Z6mk_fwd4Args.numbered_sgpr, 100
	.set _Z6mk_fwd4Args.num_named_barrier, 0
	.set _Z6mk_fwd4Args.private_seg_size, 0
	.set _Z6mk_fwd4Args.uses_vcc, 1
	.set _Z6mk_fwd4Args.uses_flat_scratch, 0
	.set _Z6mk_fwd4Args.has_dyn_sized_stack, 0
	.set _Z6mk_fwd4Args.has_recursion, 0
	.set _Z6mk_fwd4Args.has_indirect_call, 0

; __global__ void __launch_bounds__(NWAVES * 64, 2) mk_fwd(Args args) {
amdhsa.kernels:
  - .agpr_count:     0
    .args:
      - .offset:         0
        .size:           184
        .value_kind:     by_value
      - .offset:         184
        .size:           4
        .value_kind:     hidden_block_count_x
      - .offset:         188
        .size:           4
        .value_kind:     hidden_block_count_y
      - .offset:         192
        .size:           4
        .value_kind:     hidden_block_count_z
      - .offset:         196
        .size:           2
        .value_kind:     hidden_group_size_x
      - .offset:         198
        .size:           2
        .value_kind:     hidden_group_size_y
      - .offset:         200
        .size:           2
        .value_kind:     hidden_group_size_z
      - .offset:         202
        .size:           2
        .value_kind:     hidden_remainder_x
      - .offset:         204
        .size:           2
        .value_kind:     hidden_remainder_y
      - .offset:         206
        .size:           2
        .value_kind:     hidden_remainder_z
      - .offset:         224
        .size:           8
        .value_kind:     hidden_global_offset_x
      - .offset:         232
        .size:           8
        .value_kind:     hidden_global_offset_y
      - .offset:         240
        .size:           8
        .value_kind:     hidden_global_offset_z
      - .offset:         248
        .size:           2
        .value_kind:     hidden_grid_dims
      - .offset:         304
        .size:           4
        .value_kind:     hidden_dynamic_lds_size
    .group_segment_fixed_size: 0
    .kernarg_segment_align: 8
    .kernarg_segment_size: 440
    .language:       OpenCL C
    .language_version:
      - 2
      - 0
    .max_flat_workgroup_size: 512
    .name:           _Z6mk_fwd4Args
    .private_segment_fixed_size: 0
    .sgpr_count:     106
    .sgpr_spill_count: 51
    .symbol:         _Z6mk_fwd4Args.kd
    .uniform_work_group_size: 1
    .uses_dynamic_stack: false
    .vgpr_count:     253
    .vgpr_spill_count: 0
    .wavefront_size: 64
